# SSD chunk loop top: dt/decay LDS read issued before the staging writes, counted lgkmcnt(15) at its first consumer
# speedup vs baseline: 1.0029x; 1.0007x over previous
; __device__ __forceinline__ unsigned f2bf(float f) { return pk2(f, f) & 0xffffu; }
; __device__ __forceinline__ float bf2f(unsigned short h) { return __uint_as_float(((unsigned)h) << 16); }
; template <bool DRY> __device__ __forceinline__ void ssd_unit(const Args& A, char* lds, int b, int h) {
;     ...
;         const size_t m0 = rb0 + c * 64; float* DTA = DTA0 + (c & 1) * 256;
;         { const int t = tid >> 4, c8 = tid & 15;
;           *(bf16x8*)(BS + t * 136 + c8 * 8) = pre[0]; *(bf16x8*)(BS + (t + 32) * 136 + c8 * 8) = pre[1]; *(bf16x8*)(CS + t * 136 + c8 * 8) = pre[2]; *(bf16x8*)(CS + (t + 32) * 136 + c8 * 8) = pre[3];
;           const int sw0 = ((((t >> 3) ^ (c8 & 7)) << 3) + (t & 7)), sw1 = (((((t + 32) >> 3) ^ (c8 & 7)) << 3) + (t & 7));
; #pragma unroll
;           for (int e = 0; e < 8; ++e) { BST[(c8 * 8 + e) * 72 + sw0] = (bf16)pre[0][e]; BST[(c8 * 8 + e) * 72 + sw1] = (bf16)pre[1][e]; }
;           const int tx = tid >> 3, cx = tid & 7; *(bf16x8*)(XS + tx * 72 + cx * 8) = pre[4]; const float dtv = DTA[tx], wv = DTA[192 + tx]; const int sx = ((((tx >> 3) ^ cx) << 3) + (tx & 7));
; #pragma unroll
;           for (int e = 0; e < 8; ++e) { const float xd = bf2f((unsigned short)pre[4][e]) * dtv; XT[(cx * 8 + e) * 72 + sx] = (bf16)f2bf(xd); XWT[(cx * 8 + e) * 72 + sx] = (bf16)f2bf(xd * wv); } }
.LBB0_811:
	s_add_i32 s4, s0, 0xffffff00
	s_and_b32 s4, s4, 0x100
	s_lshl_b32 s4, s4, 2
	s_add_i32 s4, s4, 0
	s_add_i32 s4, s4, 0x1a400
	v_lshl_add_u32 v196, v66, 2, s4
	ds_read2st64_b32 v[198:199], v196 offset1:3
	ds_write_b128 v120, v[20:23] offset:17408
	ds_write_b128 v132, v[24:27] offset:17408
	ds_write_b128 v120, v[28:31]
	ds_write_b128 v132, v[32:35]
	ds_write_b16 v123, v20 offset:34816
	ds_write_b16 v124, v24 offset:34816
	ds_write_b16_d16_hi v123, v20 offset:34960
	ds_write_b16_d16_hi v124, v24 offset:34960
	ds_write_b16 v123, v21 offset:35104
	ds_write_b16 v124, v25 offset:35104
	ds_write_b16_d16_hi v123, v21 offset:35248
	ds_write_b16_d16_hi v124, v25 offset:35248
	ds_write_b16 v123, v22 offset:35392
	ds_write_b16 v124, v26 offset:35392
	ds_write_b16_d16_hi v123, v22 offset:35536
	ds_write_b16_d16_hi v124, v26 offset:35536
	ds_write_b16 v123, v23 offset:35680
	ds_write_b16 v124, v27 offset:35680
	ds_write_b16_d16_hi v123, v23 offset:35824
	ds_write_b16_d16_hi v124, v27 offset:35824
	ds_write_b128 v117, v[16:19]
	s_nop 0
	s_nop 0
	v_lshlrev_b32_e32 v22, 16, v16
	v_and_b32_e32 v16, 0xffff0000, v16
	v_lshl_add_u64 v[44:45], v[72:73], 0, s[54:55]
	s_waitcnt lgkmcnt(15)
	v_mul_f32_e32 v22, v198, v22
	v_cvt_pk_bf16_f32 v23, v22, s0
	v_mul_f32_e32 v22, v199, v22
	v_cvt_pk_bf16_f32 v22, v22, s0
	v_mul_f32_e32 v16, v198, v16
	ds_write_b16 v109, v22 offset:62464
	v_cvt_pk_bf16_f32 v22, v16, s0
	v_mul_f32_e32 v16, v199, v16
	v_cvt_pk_bf16_f32 v16, v16, s0
	ds_write_b16 v109, v16 offset:62608
	v_lshlrev_b32_e32 v16, 16, v17
	v_mul_f32_e32 v16, v198, v16
	ds_write_b16 v109, v22 offset:53392
	v_cvt_pk_bf16_f32 v22, v16, s0
	v_mul_f32_e32 v16, v199, v16
	v_cvt_pk_bf16_f32 v16, v16, s0
	ds_write_b16 v109, v16 offset:62752
	v_and_b32_e32 v16, 0xffff0000, v17
	v_mul_f32_e32 v16, v198, v16
	v_cvt_pk_bf16_f32 v17, v16, s0
	v_mul_f32_e32 v16, v199, v16
	v_cvt_pk_bf16_f32 v16, v16, s0
	ds_write_b16 v109, v16 offset:62896
	v_lshlrev_b32_e32 v16, 16, v18
	v_mul_f32_e32 v16, v198, v16
	ds_write_b16 v109, v17 offset:53680
	v_cvt_pk_bf16_f32 v17, v16, s0
	v_mul_f32_e32 v16, v199, v16
	v_cvt_pk_bf16_f32 v16, v16, s0
	ds_write_b16 v109, v16 offset:63040
	v_and_b32_e32 v16, 0xffff0000, v18
	v_mul_f32_e32 v16, v198, v16
	ds_write_b16 v109, v17 offset:53824
	v_cvt_pk_bf16_f32 v17, v16, s0
	v_mul_f32_e32 v16, v199, v16
	v_cvt_pk_bf16_f32 v16, v16, s0
	ds_write_b16 v109, v16 offset:63184
	v_lshlrev_b32_e32 v16, 16, v19
	v_mul_f32_e32 v16, v198, v16
	ds_write_b16 v109, v17 offset:53968
	v_cvt_pk_bf16_f32 v17, v16, s0
	v_mul_f32_e32 v16, v199, v16
	v_cvt_pk_bf16_f32 v16, v16, s0
	ds_write_b16 v109, v16 offset:63328
	v_and_b32_e32 v16, 0xffff0000, v19
	v_mul_f32_e32 v16, v198, v16
	ds_write_b16 v109, v17 offset:54112
	v_cvt_pk_bf16_f32 v17, v16, s0
	v_mul_f32_e32 v16, v199, v16
	v_cvt_pk_bf16_f32 v16, v16, s0
	ds_write_b16 v109, v16 offset:63472
	v_add_co_u32_e32 v16, vcc, 0x1b00000, v44
	ds_write_b16 v109, v17 offset:54256
	s_nop 0
	v_addc_co_u32_e32 v17, vcc, 0, v45, vcc
	ds_write_b16 v109, v23 offset:53248
	ds_write_b16 v109, v22 offset:53536
	flat_store_short v[16:17], v151
	v_lshl_add_u64 v[16:17], v[78:79], 0, s[56:57]
	s_and_saveexec_b64 s[66:67], s[28:29]
	s_cbranch_execz .LBB0_813
	flat_store_dword v[16:17], v42 offset:3072
